# v44 + sub-phase reorder for Infinity-Cache reuse: P9 row pass before weight quantisation, P4 rotq pass before RG-LRU
# baseline (speedup 1.0000x reference)
; #define LAS __attribute__((address_space(3)))
; #define P4_BODY do { \
;         lru_fused(XC, Wrg_t, PROJ, YL, b_rg_a, b_rg_x, sp8, lds, tid, lane, wave, vcu, G); } while (0)
; __device__ __forceinline__ void lru_fused(const bf16* XC, const bf16* Wrg_t, const bf16* PROJ, bf16* YL, const float* b_a, const float* b_x, const float* sp8,
;                                           LAS unsigned char* lds, int tid, int lane, int wave, int vcu, int G) {
;     ...
;     for (int vq = vcu; vq < 256; vq += G) {
;         const int h = vq >> 4, s = (vq >> 1) & 7, bsel = vq & 1;
;         __syncthreads();
;         { const int n = tid >> 3, p = tid & 7, chl = s * 32 + (n & 31), srow = h * 512 + (chl >> 7) * 256 + (n >> 5) * 128 + (chl & 127);
;           const v4u* src = (const v4u*)(Wrg_t + (size_t)srow * HD + p * 32); LAS v4u* dst = (LAS v4u*)(lds + n * RG_PITCH + p * 64);
; #pragma unroll
;           for (int q = 0; q < 4; ++q) dst[q] = src[q]; }
;         __syncthreads();
;         const int c0 = h * HD + s * 32;
;         f32x4 ba[2], bx[2], sp[2];
; #pragma unroll
;         for (int c2 = 0; c2 < 2; ++c2) { const int ch = c0 + 16 * c2 + 4 * fq; ba[c2] = *(const f32x4*)(b_a + ch); bx[c2] = *(const f32x4*)(b_x + ch); sp[c2] = *(const f32x4*)(sp8 + ch) * 1.44269504088896f; }
;         const bf16* abase = XC + h * HD + 8 * fq; const bf16* xbase = XC + c0 + 4 * fq; const bf16* gbase = PROJ + D + c0 + 4 * fq; bf16* obase = YL + c0 + 4 * fq;
;         const LAS unsigned char* bl = lds + fr * RG_PITCH + 16 * fq;
;         LAS float* xch = (LAS float*)(lds + LRU_XOFF);
; __global__ void __launch_bounds__(NWAVES * 64, 2) fwd_kernel(Args args) {
;     ...
;     if (IN(4)) {
;     ...
;         P4_BODY; if (DUP(4)) { P4_BODY; }
.LBB0_450:
	s_add_u32 s0, s12, 0x46e00000
	s_addc_u32 s1, s13, 0
	s_add_u32 s4, s12, 0x46e10000
	s_addc_u32 s5, s13, 0
	s_cmp_lt_i32 s28, 5
	s_cselect_b64 s[2:3], -1, 0
	s_cmp_gt_i32 s29, 4
	s_cselect_b64 s[6:7], -1, 0
	s_and_b64 s[2:3], s[2:3], s[6:7]
	s_mov_b64 s[78:79], s[12:13]
	s_andn2_b64 vcc, exec, s[2:3]
	s_cbranch_vccnz .LBB0_537
	s_branch .LBB0_478
.Lp4_A:
	s_waitcnt lgkmcnt(0)
	s_barrier
	s_cmpk_gt_i32 s34, 0xff
	s_cbranch_scc1 .LBB0_483
	s_waitcnt vmcnt(0)
	v_and_b32_e32 v2, 7, v0
	v_lshlrev_b32_e32 v4, 6, v2
	v_mov_b32_e32 v2, 0
	v_readlane_b32 s2, v249, 25
	v_mov_b32_e32 v5, v2
	v_readlane_b32 s3, v249, 26
	v_lshrrev_b32_e32 v3, 4, v178
	v_lshrrev_b32_e32 v6, 3, v0
	v_lshl_add_u64 v[112:113], s[2:3], 0, v[4:5]
	s_movk_i32 s6, 0x220
	v_readlane_b32 s2, v249, 35
	v_mad_u32_u24 v5, v6, s6, 0
	v_lshlrev_b32_e32 v6, 3, v3
	v_mov_b32_e32 v7, v2
	v_and_b32_e32 v8, 48, v178
	v_mov_b32_e32 v9, v2
	v_readlane_b32 s3, v249, 36
	s_mov_b64 s[16:17], s[78:79]
	v_and_b32_e32 v110, 15, v0
	v_lshl_add_u64 v[114:115], s[2:3], 0, v[8:9]
	v_lshl_add_u64 v[116:117], s[2:3], 0, v[6:7]
	v_lshl_add_u64 v[6:7], s[16:17], 0, v[6:7]
	s_mov_b64 s[2:3], 0x18e02000
	v_lshl_add_u64 v[118:119], v[6:7], 0, s[2:3]
	v_readlane_b32 s2, v249, 38
	v_lshlrev_b32_e32 v165, 2, v3
	v_mad_u32_u24 v3, v110, s6, 0
	s_mov_b32 s8, s2
	s_lshl_b32 s6, s2, 5
	s_cmp_eq_u32 s8, 7
	s_cselect_b64 s[12:13], -1, 0
	v_cmp_eq_u32_e32 vcc, 0, v110
	s_and_b64 s[40:41], vcc, s[12:13]
	v_readlane_b32 s7, v249, 37
	s_cmp_gt_u32 s7, 63
	s_cselect_b64 s[42:43], -1, 0
	s_cmpk_gt_u32 s7, 0x7f
	s_cselect_b64 s[44:45], -1, 0
	s_cmpk_gt_u32 s7, 0xbf
	v_and_b32_e32 v9, 48, v0
	s_cselect_b64 s[48:49], -1, 0
	s_cmpk_gt_u32 s7, 0xff
	s_cselect_b64 s[50:51], -1, 0
	s_cmpk_gt_u32 s7, 0x13f
	v_add_u32_e32 v170, v3, v9
	v_mbcnt_lo_u32_b32 v3, -1, 0
	v_lshrrev_b32_e32 v10, 1, v0
	s_cselect_b64 s[52:53], -1, 0
	s_cmpk_gt_u32 s7, 0x17f
	v_mbcnt_hi_u32_b32 v3, -1, v3
	v_readlane_b32 s3, v249, 39
	v_or_b32_e32 v166, s6, v110
	v_readlane_b32 s36, v249, 31
	s_cselect_b64 s[54:55], -1, 0
	s_cmpk_gt_u32 s7, 0x1bf
	v_and_b32_e32 v6, 24, v10
	v_mov_b32_e32 v7, v2
	v_and_or_b32 v3, v3, 64, v178
	v_bfe_u32 v1, v0, 3, 5
	v_and_b32_e32 v164, 0x80, v10
	s_mov_b32 s39, 0
	v_mov_b32_e32 v111, v2
	v_add_u32_e32 v167, 0, v8
	v_cmp_eq_u32_e64 s[2:3], 15, v110
	v_readlane_b32 s37, v249, 32
	s_cselect_b64 s[58:59], -1, 0
	v_lshl_add_u64 v[120:121], s[16:17], 0, v[6:7]
	v_or_b32_e32 v168, 16, v166
	s_lshl_b32 s7, s34, 13
	s_lshl_b32 s8, s10, 13
	s_lshl_b32 s11, s34, 4
	s_lshl_b32 s12, s10, 4
	v_add_u32_e32 v169, v5, v4
	s_mov_b32 s62, 0x3fb8aa3b
	s_mov_b32 s13, 0xa000
	s_mov_b32 s16, 0xa0000
	v_mov_b32_e32 v171, 0xc0135761
	s_mov_b32 s17, 0x50e00000
	v_lshl_or_b32 v172, v3, 2, 60
	s_mov_b32 s18, s34
	s_branch .LBB0_454

; #define LAS __attribute__((address_space(3)))
; #define REP(k) _Pragma("unroll 1") for (int rep_ = 0; rep_ < DUP(k) + 1; ++rep_)
; template <class MapF>
; __device__ __forceinline__ void strip_quant(const float* W, int ldw, unsigned char* W8o, float* cso, int nstrips, int s0, int sstride, LAS unsigned char* lds, int lane, int wave, const MapF map) {
;     LAS unsigned char* sbuf = lds; LAS float* red = (LAS float*)(lds + RING_BYTES + 8192);
;     const int nn = lane & 15, kh = lane >> 4;
;     const float s16 = (kh & 1) ? -1.f : 1.f, s32 = (kh & 2) ? -0.125f : 0.125f;
;     float va[16], vb[16];
;     if (s0 >= nstrips) return;
;     int n0, drow0; map(s0, n0, drow0);
;     const float* wp = W + (size_t)(512 * wave + 16 * kh) * ldw + n0 + nn;
; #pragma unroll
;     for (int i = 0; i < 16; ++i) { va[i] = wp[(size_t)i * ldw]; vb[i] = wp[(size_t)(64 + i) * ldw]; }
; __global__ void __launch_bounds__(NWAVES * 64, 2) fwd_kernel(Args args) {
;     ...
;     if (IN(9)) REP(9) {
;         {
;             LAS float* scr = (LAS float*)(lds + wave * 16384);
;             int itbase = 0;
;             (void)itbase;
;             strip_quant(w_gu, NGU, W8gu, cscalef, NGU / 16, vcu, G, lds, lane, wave, SMapGU{});
.LBB0_721:
	s_mov_b64 s[0:1], s[78:79]
	s_add_u32 s40, s0, 0xc0000
	s_addc_u32 s41, s1, 0
	s_add_u32 s48, s0, 0x4ce00000
	s_addc_u32 s49, s1, 0
	s_add_u32 s50, s0, 0x4ce10000
	s_addc_u32 s51, s1, 0
	s_add_u32 s42, s0, 0x23a00000
	s_addc_u32 s43, s1, 0
	s_add_u32 s38, s0, 0x48e00000
	s_addc_u32 s39, s1, 0
	s_cmp_lt_i32 s28, 10
	s_cselect_b64 s[0:1], -1, 0
	s_cmp_gt_i32 s29, 9
	s_cselect_b64 s[2:3], -1, 0
	s_and_b64 s[0:1], s[0:1], s[2:3]
	s_andn2_b64 vcc, exec, s[0:1]
	s_cbranch_vccnz .LBB0_831
	s_branch .LBB0_768
.Lp9_A:
	s_waitcnt lgkmcnt(0)
	s_barrier
	v_readlane_b32 s0, v249, 38
	v_readlane_b32 s1, v249, 39
	s_lshl_b32 s1, s0, 14
	s_waitcnt vmcnt(0)
	v_mov_b32_e32 v1, 0xbe000000
	v_mov_b32_e32 v2, 0x3e000000
	v_cmp_gt_u32_e64 s[2:3], 32, v178
	s_mov_b32 s0, 0x3e000000
	s_cmpk_gt_i32 s34, 0x55f
	v_cndmask_b32_e64 v34, v1, v2, s[2:3]
	s_cbranch_scc1 .LBB0_737
	v_readlane_b32 s52, v249, 43
	v_readlane_b32 s60, v249, 51
	v_readlane_b32 s61, v249, 52
	v_readlane_b32 s62, v249, 53
	v_readlane_b32 s63, v249, 54
	v_readlane_b32 s64, v249, 55
	v_readlane_b32 s65, v249, 56
	v_readlane_b32 s66, v249, 57
	v_readlane_b32 s67, v249, 58
	s_mov_b64 s[20:21], s[60:61]
	s_mov_b64 s[22:23], s[62:63]
	v_and_b32_e32 v1, 48, v0
	v_readlane_b32 s4, v249, 38
	v_mov_b32_e32 v2, s22
	v_mov_b32_e32 v3, s23
	v_readlane_b32 s5, v249, 39
	v_lshl_or_b32 v18, s4, 9, v1
	s_mov_b32 s4, 0x15800
	v_mad_i64_i32 v[22:23], s[4:5], v18, s4, v[2:3]
	v_readlane_b32 s4, v249, 37
	s_add_i32 s7, 0, 0x22000
	s_and_b32 s6, s4, 0xffffffc0
	s_cmp_lt_u32 s4, 64
	v_readlane_b32 s53, v249, 44
	s_cselect_b64 s[22:23], -1, 0
	s_lshl_b32 s52, s34, 4
	v_and_b32_e32 v36, 15, v0
	s_ashr_i32 s53, s52, 31
	v_mov_b32_e32 v21, 0
	v_lshlrev_b32_e32 v20, 2, v36
	v_lshl_add_u64 v[2:3], s[52:53], 2, v[22:23]
	v_lshl_add_u64 v[38:39], v[2:3], 0, v[20:21]
	s_mov_b32 s4, 0x560000
	v_add_co_u32_e32 v2, vcc, s4, v38
	s_mov_b32 s4, 0x575000
	s_nop 0
	v_addc_co_u32_e32 v3, vcc, 0, v39, vcc
	v_add_co_u32_e32 v4, vcc, s4, v38
	s_mov_b32 s4, 0x58b000
	s_nop 0
	v_addc_co_u32_e32 v5, vcc, 0, v39, vcc
	v_add_co_u32_e32 v6, vcc, s4, v38
	s_mov_b32 s4, 0x5a0000
	s_nop 0
	v_addc_co_u32_e32 v7, vcc, 0, v39, vcc
	v_add_co_u32_e32 v8, vcc, s4, v38
	s_mov_b32 s4, 0x5b6000
	s_nop 0
	v_addc_co_u32_e32 v9, vcc, 0, v39, vcc
	v_add_co_u32_e32 v10, vcc, s4, v38
	s_mov_b32 s4, 0x5cb000
	s_nop 0
	v_addc_co_u32_e32 v11, vcc, 0, v39, vcc
	v_add_co_u32_e32 v12, vcc, s4, v38
	s_mov_b32 s4, 0x5e1000
	s_nop 0
	v_addc_co_u32_e32 v13, vcc, 0, v39, vcc
	v_add_co_u32_e32 v14, vcc, s4, v38
	s_mov_b32 s4, 0x5f6000
	s_nop 0
	v_addc_co_u32_e32 v15, vcc, 0, v39, vcc
	v_add_co_u32_e32 v16, vcc, s4, v38
	s_mov_b32 s4, 0x60c000
	s_nop 0
	v_addc_co_u32_e32 v17, vcc, 0, v39, vcc
	global_load_dword v44, v[2:3], off
	global_load_dword v45, v[4:5], off offset:2048
	global_load_dword v48, v[6:7], off
	global_load_dword v49, v[8:9], off offset:2048
	global_load_dword v50, v[10:11], off
	global_load_dword v51, v[12:13], off offset:2048
	global_load_dword v52, v[14:15], off
	global_load_dword v53, v[16:17], off offset:2048
	v_add_co_u32_e32 v2, vcc, s4, v38
	s_mov_b32 s4, 0x621000
	s_nop 0
	v_addc_co_u32_e32 v3, vcc, 0, v39, vcc
	v_add_co_u32_e32 v4, vcc, s4, v38
	s_mov_b32 s4, 0x637000
	s_nop 0
	v_addc_co_u32_e32 v5, vcc, 0, v39, vcc
	v_add_co_u32_e32 v6, vcc, s4, v38
	s_mov_b32 s4, 0x64c000
	s_nop 0
	v_addc_co_u32_e32 v7, vcc, 0, v39, vcc
	v_add_co_u32_e32 v8, vcc, s4, v38
	s_mov_b32 s4, 0x662000
	s_nop 0
	v_addc_co_u32_e32 v9, vcc, 0, v39, vcc
	v_add_co_u32_e32 v10, vcc, s4, v38
	s_mov_b32 s4, 0x677000
	s_nop 0
	v_addc_co_u32_e32 v11, vcc, 0, v39, vcc
	v_add_co_u32_e32 v12, vcc, s4, v38
	s_mov_b32 s4, 0x68d000
	s_nop 0
	v_addc_co_u32_e32 v13, vcc, 0, v39, vcc
	v_add_co_u32_e32 v14, vcc, s4, v38
	s_mov_b32 s4, 0x6a2000
	s_nop 0
	v_addc_co_u32_e32 v15, vcc, 0, v39, vcc
	v_add_co_u32_e32 v16, vcc, s4, v38
	s_mov_b32 s4, 0x15000
	s_nop 0
	v_addc_co_u32_e32 v17, vcc, 0, v39, vcc
	global_load_dword v54, v[2:3], off
	global_load_dword v55, v[4:5], off offset:2048
	global_load_dword v56, v[6:7], off
	global_load_dword v57, v[8:9], off offset:2048
	global_load_dword v58, v[10:11], off
	global_load_dword v59, v[12:13], off offset:2048
	global_load_dword v60, v[14:15], off
	global_load_dword v61, v[16:17], off offset:2048
	v_add_co_u32_e32 v2, vcc, s4, v38
	s_mov_b32 s4, 0x2b000
; #define LAS __attribute__((address_space(3)))
; template <class MapF>
; __device__ __forceinline__ void strip_quant(const float* W, int ldw, unsigned char* W8o, float* cso, int nstrips, int s0, int sstride, LAS unsigned char* lds, int lane, int wave, const MapF map) {
;     LAS unsigned char* sbuf = lds; LAS float* red = (LAS float*)(lds + RING_BYTES + 8192);
;     const int nn = lane & 15, kh = lane >> 4;
;     const float s16 = (kh & 1) ? -1.f : 1.f, s32 = (kh & 2) ? -0.125f : 0.125f;
;     float va[16], vb[16];
;     if (s0 >= nstrips) return;
;     int n0, drow0; map(s0, n0, drow0);
;     const float* wp = W + (size_t)(512 * wave + 16 * kh) * ldw + n0 + nn;
; #pragma unroll
;     for (int i = 0; i < 16; ++i) { va[i] = wp[(size_t)i * ldw]; vb[i] = wp[(size_t)(64 + i) * ldw]; }
	s_nop 0
	v_addc_co_u32_e32 v3, vcc, 0, v39, vcc
	v_add_co_u32_e32 v4, vcc, s4, v38
	s_mov_b32 s4, 0x40000
	s_nop 0
	v_addc_co_u32_e32 v5, vcc, 0, v39, vcc
	v_add_co_u32_e32 v6, vcc, s4, v38
	s_mov_b32 s4, 0x56000
	s_nop 0
	v_addc_co_u32_e32 v7, vcc, 0, v39, vcc
	v_add_co_u32_e32 v8, vcc, s4, v38
	s_mov_b32 s4, 0x6b000
	s_nop 0
	v_addc_co_u32_e32 v9, vcc, 0, v39, vcc
	v_add_co_u32_e32 v10, vcc, s4, v38
	s_mov_b32 s4, 0x81000
	s_nop 0
	v_addc_co_u32_e32 v11, vcc, 0, v39, vcc
	v_add_co_u32_e32 v12, vcc, s4, v38
	s_mov_b32 s4, 0x96000
	s_nop 0
	v_addc_co_u32_e32 v13, vcc, 0, v39, vcc
	v_add_co_u32_e32 v14, vcc, s4, v38
	s_mov_b32 s4, 0xac000
	s_nop 0
	v_addc_co_u32_e32 v15, vcc, 0, v39, vcc
	v_add_co_u32_e32 v16, vcc, s4, v38
	s_mov_b32 s4, 0xc1000
	s_nop 0
	v_addc_co_u32_e32 v17, vcc, 0, v39, vcc
	global_load_dword v3, v[2:3], off offset:2048
	s_nop 0
	global_load_dword v4, v[4:5], off
	s_nop 0
	global_load_dword v5, v[6:7], off offset:2048
	s_nop 0
	global_load_dword v6, v[8:9], off
	global_load_dword v7, v[10:11], off offset:2048
	s_nop 0
	global_load_dword v8, v[12:13], off
	global_load_dword v9, v[14:15], off offset:2048
	global_load_dword v10, v[16:17], off
	v_add_co_u32_e32 v12, vcc, s4, v38
	s_mov_b32 s4, 0xd7000
	s_nop 0
	v_addc_co_u32_e32 v13, vcc, 0, v39, vcc
	v_add_co_u32_e32 v14, vcc, s4, v38
	s_mov_b32 s4, 0xec000
	s_nop 0
	v_addc_co_u32_e32 v15, vcc, 0, v39, vcc
	v_add_co_u32_e32 v16, vcc, s4, v38
	s_mov_b32 s4, 0x102000
	s_nop 0
	v_addc_co_u32_e32 v17, vcc, 0, v39, vcc
	v_add_co_u32_e32 v24, vcc, s4, v38
	s_mov_b32 s4, 0x117000
	s_nop 0
	v_addc_co_u32_e32 v25, vcc, 0, v39, vcc
	v_add_co_u32_e32 v26, vcc, s4, v38
	s_mov_b32 s4, 0x12d000
	s_nop 0
	v_addc_co_u32_e32 v27, vcc, 0, v39, vcc
	v_add_co_u32_e32 v28, vcc, s4, v38
	s_mov_b32 s4, 0x142000
	s_nop 0
	v_addc_co_u32_e32 v29, vcc, 0, v39, vcc
	v_add_co_u32_e32 v30, vcc, s4, v38
	v_and_b32_e32 v1, 16, v0
	s_nop 0
	v_addc_co_u32_e32 v31, vcc, 0, v39, vcc
	global_load_dword v2, v[38:39], off
	global_load_dword v11, v[12:13], off offset:2048
	s_nop 0
	global_load_dword v12, v[14:15], off
	global_load_dword v13, v[16:17], off offset:2048
	s_nop 0
	global_load_dword v14, v[24:25], off
	global_load_dword v15, v[26:27], off offset:2048
	global_load_dword v16, v[28:29], off
	global_load_dword v17, v[30:31], off offset:2048
	v_mbcnt_lo_u32_b32 v29, -1, 0
	v_mbcnt_hi_u32_b32 v29, -1, v29
	v_cmp_gt_u32_e64 s[4:5], 16, v178
	v_and_b32_e32 v31, 64, v29
	v_cmp_eq_u32_e32 vcc, 0, v1
	v_lshl_add_u64 v[42:43], v[22:23], 0, v[20:21]
	v_lshl_add_u32 v21, v178, 2, s7
	v_add_u32_e32 v1, s7, v20
	s_and_b64 s[22:23], s[4:5], s[22:23]
	s_and_b32 s7, s52, 0x70
	v_xor_b32_e32 v30, 16, v29
	v_add_u32_e32 v31, 64, v31
	v_cndmask_b32_e64 v40, -1.0, 1.0, vcc
	s_cmpk_gt_i32 s34, 0x2af
	v_cmp_lt_i32_e32 vcc, v30, v31
	v_ashrrev_i32_e32 v19, 31, v18
	s_cselect_b32 s11, 0xffffd500, 0
	v_cndmask_b32_e32 v30, v29, v30, vcc
	v_or_b32_e32 v20, v18, v36
	s_cselect_b32 s8, 0x80, 0
	s_add_i32 s11, s11, s52
	v_lshlrev_b32_e32 v64, 2, v30
	v_xor_b32_e32 v30, 32, v29
	v_lshl_add_u64 v[46:47], s[96:97], 0, v[18:19]
	v_lshlrev_b32_e32 v18, 5, v178
	v_lshlrev_b32_e32 v37, 5, v20
	s_or_b32 s7, s7, s8
	s_lshl_b32 s8, s11, 1
	v_cmp_lt_i32_e32 vcc, v30, v31
	v_and_b32_e32 v18, 0x600, v18
	v_lshlrev_b32_e32 v22, 5, v36
	v_or_b32_e32 v20, 0x800, v37
	v_or_b32_e32 v23, 0x1000, v37
	v_or_b32_e32 v24, 0x1800, v37
	v_or_b32_e32 v25, 0x2000, v37
	v_or_b32_e32 v26, 0x2800, v37
	v_or_b32_e32 v27, 0x3000, v37
	v_or_b32_e32 v28, 0x3800, v37
	s_and_b32 s8, s8, 0xffffff00
	v_cndmask_b32_e32 v29, v29, v30, vcc
	v_add_u32_e32 v18, s1, v18
	s_or_b32 s16, s7, s8
	v_lshlrev_b32_e32 v65, 2, v29
	v_mov_b32_e32 v41, v40
	v_mov_b32_e32 v35, v34
	v_add3_u32 v66, v18, v22, 0
	v_add_u32_e32 v67, s6, v21
	s_mov_b32 s6, 0xda24260
	s_mov_b32 s7, 0x42fe0000
	s_mov_b32 s8, 0xc0c0400
	s_mov_b32 s11, 0x5040100
	v_add_u32_e32 v68, 0, v20
	v_add_u32_e32 v69, 0, v23
	v_add_u32_e32 v70, 0, v24
	v_add_u32_e32 v71, 0, v25
	v_add_u32_e32 v72, 0, v26
	v_add_u32_e32 v73, 0, v27
	v_add_u32_e32 v74, 0, v28
	s_mov_b32 s12, s34
	v_readlane_b32 s54, v249, 45
	v_readlane_b32 s55, v249, 46
	v_readlane_b32 s56, v249, 47
	v_readlane_b32 s57, v249, 48
	v_readlane_b32 s58, v249, 49
	v_readlane_b32 s59, v249, 50
	s_mov_b64 s[24:25], s[64:65]
	s_mov_b64 s[26:27], s[66:67]
	s_branch .LBB0_725
